# phase-3 conversion tail rebalanced: 4-unit workgroups take the last 176 weight blocks (N1=448), packed norm rows
# baseline (speedup 1.0000x reference)
.LBB0_330:
	s_abs_i32 s66, s84
	v_cvt_f32_u32_e32 v1, s66
	s_sub_i32 s0, 0, s66
	v_readlane_b32 s82, v254, 9
	v_rcp_iflag_f32_e32 v1, v1
	s_nop 0
	v_mul_f32_e32 v1, 0x4f7ffffe, v1
	v_cvt_u32_f32_e32 v1, v1
	s_nop 0
	v_readfirstlane_b32 s67, v1
	s_mul_i32 s0, s0, s67
	s_mul_hi_u32 s0, s67, s0
	s_add_i32 s67, s67, s0
	s_mul_hi_u32 s0, s67, 0x3c0
	s_mul_i32 s0, s0, s66
	s_sub_i32 s0, 0x3c0, s0
	s_sub_i32 s1, s0, s66
	s_cmp_ge_u32 s0, s66
	s_cselect_b32 s0, s1, s0
	s_sub_i32 s1, s0, s66
	s_cmp_ge_u32 s0, s66
	s_cselect_b32 s3, s1, s0
	s_cmp_lt_i32 s83, s3
	s_cbranch_scc1 .Ltail0_unitwg
	s_sub_i32 s2, s83, s3
	s_movk_i32 s98, 0x1c0
	s_cmp_eq_u32 s3, 0
	s_cselect_b32 s98, 0x270, s98
	s_sub_i32 s99, s84, s3
	s_branch .Ltail0_common
.Ltail0_unitwg:
	s_add_i32 s2, s83, 0x1c0
	s_movk_i32 s98, 0x270
	s_mov_b32 s99, s3
.Ltail0_common:
	s_cmp_ge_i32 s2, s98
	s_cbranch_scc1 .LBB0_415
	v_readlane_b32 s4, v254, 0
	v_readlane_b32 s5, v254, 1
	s_load_dwordx2 s[0:1], s[4:5], 0xf0
	s_mov_b32 s3, s99
	s_load_dwordx2 s[6:7], s[4:5], 0xe0
	s_load_dwordx2 s[22:23], s[4:5], 0xc8
	s_load_dwordx4 s[8:11], s[4:5], 0x40
	s_load_dwordx2 s[28:29], s[4:5], 0x50
	s_load_dwordx4 s[12:15], s[4:5], 0xb0
	s_load_dwordx4 s[16:19], s[4:5], 0x78
	s_movk_i32 s55, 0x1f0
	s_waitcnt lgkmcnt(0)
	s_add_u32 s33, s0, 0x2c80000
	s_addc_u32 s50, s1, 0
	s_add_u32 s51, s0, 0x1680000
	s_addc_u32 s52, s1, 0
	s_add_u32 s24, s0, 0x1480000
	s_addc_u32 s25, s1, 0
	s_add_u32 s26, s0, 0xe80000
	s_addc_u32 s27, s1, 0
	s_add_u32 s30, s0, 0xb80000
	s_addc_u32 s31, s1, 0
	s_add_u32 s34, s0, 0x400000
	s_addc_u32 s35, s1, 0
	s_add_u32 s53, s0, 0x78000
	s_addc_u32 s54, s1, 0
	s_mov_b32 s37, 0
	v_mov_b32_e32 v87, 0
	s_movk_i32 s56, 0x404
	s_movk_i32 s57, 0xfa50
	s_mov_b32 s58, 0x3780000
	s_mov_b64 s[38:39], 0x1000
	s_mov_b32 s59, 0x4080000
	s_movk_i32 s60, 0x104
	s_movk_i32 s61, 0x3c00
	s_mov_b32 s62, 0x20000
	s_mov_b32 s63, 0x40000
	s_movk_i32 s64, 0x47f
	s_movk_i32 s65, 0x27f
	s_movk_i32 s68, 0x6000
	s_mov_b32 s69, 0xc000
	s_mov_b32 s71, 0x12000
	s_mov_b32 s72, 0x18000
	s_mov_b32 s73, 0x1e000
	s_mov_b32 s74, 0x24000
	s_mov_b32 s75, 0x2a000
	s_movk_i32 s76, 0x2400
	s_movk_i32 s77, 0x900
	s_movk_i32 s78, 0x1ff
	s_movk_i32 s79, 0x6ff
	v_mov_b32_e32 v1, 0x3e000000
	s_branch .LBB0_335
.LBB0_333:
	s_or_b64 exec, exec, s[40:41]
	s_barrier
.LBB0_334:
	s_add_i32 s2, s2, s3
	s_cmp_lt_i32 s2, s98
	s_cbranch_scc0 .LBB0_415
.LBB0_335:
	s_cmpk_lt_i32 s2, 0x310
	s_mov_b64 s[4:5], -1
	s_cbranch_scc0 .LBB0_371
	s_cmpk_lt_u32 s2, 0x1c0
	s_cselect_b32 s4, s55, 0x350
	s_cmpk_gt_i32 s2, 0x5f
	s_cselect_b32 s4, s4, 0xf0
	s_add_i32 s81, s4, s2
	s_cmpk_lt_i32 s81, 0xf0
	s_cselect_b64 s[40:41], -1, 0
	s_mov_b64 s[4:5], -1
	s_and_b64 vcc, exec, s[40:41]
	s_cbranch_vccnz .LBB0_344
	s_cmpk_gt_u32 s81, 0x14f
	s_cbranch_scc0 .LBB0_345
	s_cmpk_gt_u32 s81, 0x20f
	s_cbranch_scc0 .LBB0_346
	s_cmpk_gt_u32 s81, 0x24f
	s_cbranch_scc0 .LBB0_347
	s_mov_b64 s[46:47], -1
	s_cmpk_gt_u32 s81, 0x50f
	s_mov_b64 s[48:49], -1
	s_cbranch_scc0 .LBB0_342
	s_add_i32 s36, s81, 0xfffffaf0
	s_add_i32 s42, s81, 0xfffffa40
	s_cmpk_lt_u32 s36, 0xb0
	s_cselect_b32 s82, s36, s42
	s_cmpk_gt_u32 s36, 0xaf
	s_cselect_b32 s36, 0xb00000, 0
	s_cselect_b32 s44, 0x580000, 0
	s_add_u32 s42, s6, s36
	s_addc_u32 s43, s7, 0
	s_add_u32 s44, s33, s44
	s_addc_u32 s45, s50, 0
	s_mov_b64 s[48:49], 0

.LBB0_834:
	s_or_b64 exec, exec, s[18:19]
	v_and_b32_e32 v10, 63, v0
	v_lshlrev_b32_e32 v62, 5, v10
	v_lshlrev_b32_e32 v11, 3, v10
	v_add_u32_e32 v12, s36, v1
	v_lshl_add_u32 v12, v12, 11, v11
	v_mov_b32_e32 v13, 0
	v_lshl_add_u64 v[14:15], v[12:13], 0, v[20:21]
	v_lshl_add_u64 v[16:17], v[12:13], 0, v[22:23]
	v_add_u32_e32 v12, 0x1000, v12
	v_lshl_add_u64 v[8:9], v[12:13], 0, v[20:21]
	v_lshl_add_u64 v[10:11], v[12:13], 0, v[22:23]
	global_load_dwordx4 v[64:67], v[14:15], off
	global_load_dwordx4 v[68:71], v[14:15], off offset:1024
	global_load_dwordx4 v[72:75], v[14:15], off offset:2048
	global_load_dwordx4 v[76:79], v[14:15], off offset:3072
	global_load_dwordx4 v[80:83], v[8:9], off
	global_load_dwordx4 v[84:87], v[8:9], off offset:1024
	global_load_dwordx4 v[88:91], v[8:9], off offset:2048
	global_load_dwordx4 v[92:95], v[8:9], off offset:3072
	s_waitcnt lgkmcnt(0)
	s_barrier
	ds_read_b128 v[96:99], v62 offset:4096
	ds_read_b128 v[100:103], v62 offset:4112
	ds_read_b128 v[104:107], v62 offset:6144
	ds_read_b128 v[108:111], v62 offset:6160
	ds_read_b128 v[112:115], v62
	ds_read_b128 v[116:119], v62 offset:16
	ds_read_b128 v[40:43], v62 offset:2048
	ds_read_b128 v[44:47], v62 offset:2064
	s_waitcnt vmcnt(6)
	v_lshlrev_b32_e32 v26, 16, v64
	v_and_b32_e32 v27, 0xffff0000, v64
	v_pk_mul_f32 v[2:3], v[26:27], v[26:27]
	v_lshlrev_b32_e32 v26, 16, v65
	v_and_b32_e32 v27, 0xffff0000, v65
	v_pk_fma_f32 v[2:3], v[26:27], v[26:27], v[2:3]
	v_lshlrev_b32_e32 v26, 16, v66
	v_and_b32_e32 v27, 0xffff0000, v66
	v_pk_fma_f32 v[2:3], v[26:27], v[26:27], v[2:3]
	v_lshlrev_b32_e32 v26, 16, v67
	v_and_b32_e32 v27, 0xffff0000, v67
	v_pk_fma_f32 v[2:3], v[26:27], v[26:27], v[2:3]
	v_lshlrev_b32_e32 v26, 16, v68
	v_and_b32_e32 v27, 0xffff0000, v68
	v_pk_fma_f32 v[2:3], v[26:27], v[26:27], v[2:3]
	v_lshlrev_b32_e32 v26, 16, v69
	v_and_b32_e32 v27, 0xffff0000, v69
	v_pk_fma_f32 v[2:3], v[26:27], v[26:27], v[2:3]
	v_lshlrev_b32_e32 v26, 16, v70
	v_and_b32_e32 v27, 0xffff0000, v70
	v_pk_fma_f32 v[2:3], v[26:27], v[26:27], v[2:3]
	v_lshlrev_b32_e32 v26, 16, v71
	v_and_b32_e32 v27, 0xffff0000, v71
	v_pk_fma_f32 v[2:3], v[26:27], v[26:27], v[2:3]
	v_add_f32_e32 v4, v2, v3
	s_waitcnt vmcnt(4)
	v_lshlrev_b32_e32 v26, 16, v72
	v_and_b32_e32 v27, 0xffff0000, v72
	v_pk_mul_f32 v[24:25], v[26:27], v[26:27]
	v_lshlrev_b32_e32 v26, 16, v73
	v_and_b32_e32 v27, 0xffff0000, v73
	v_pk_fma_f32 v[24:25], v[26:27], v[26:27], v[24:25]
	v_lshlrev_b32_e32 v26, 16, v74
	v_and_b32_e32 v27, 0xffff0000, v74
	v_pk_fma_f32 v[24:25], v[26:27], v[26:27], v[24:25]
	v_lshlrev_b32_e32 v26, 16, v75
	v_and_b32_e32 v27, 0xffff0000, v75
	v_pk_fma_f32 v[24:25], v[26:27], v[26:27], v[24:25]
	v_lshlrev_b32_e32 v26, 16, v76
	v_and_b32_e32 v27, 0xffff0000, v76
	v_pk_fma_f32 v[24:25], v[26:27], v[26:27], v[24:25]
	v_lshlrev_b32_e32 v26, 16, v77
	v_and_b32_e32 v27, 0xffff0000, v77
	v_pk_fma_f32 v[24:25], v[26:27], v[26:27], v[24:25]
	v_lshlrev_b32_e32 v26, 16, v78
	v_and_b32_e32 v27, 0xffff0000, v78
	v_pk_fma_f32 v[24:25], v[26:27], v[26:27], v[24:25]
	v_lshlrev_b32_e32 v26, 16, v79
	v_and_b32_e32 v27, 0xffff0000, v79
	v_pk_fma_f32 v[24:25], v[26:27], v[26:27], v[24:25]
	v_add_f32_e32 v5, v24, v25
	s_waitcnt vmcnt(2)
	v_lshlrev_b32_e32 v26, 16, v80
	v_and_b32_e32 v27, 0xffff0000, v80
	v_pk_mul_f32 v[120:121], v[26:27], v[26:27]
	v_lshlrev_b32_e32 v26, 16, v81
	v_and_b32_e32 v27, 0xffff0000, v81
	v_pk_fma_f32 v[120:121], v[26:27], v[26:27], v[120:121]
	v_lshlrev_b32_e32 v26, 16, v82
	v_and_b32_e32 v27, 0xffff0000, v82
	v_pk_fma_f32 v[120:121], v[26:27], v[26:27], v[120:121]
	v_lshlrev_b32_e32 v26, 16, v83
	v_and_b32_e32 v27, 0xffff0000, v83
	v_pk_fma_f32 v[120:121], v[26:27], v[26:27], v[120:121]
	v_lshlrev_b32_e32 v26, 16, v84
	v_and_b32_e32 v27, 0xffff0000, v84
	v_pk_fma_f32 v[120:121], v[26:27], v[26:27], v[120:121]
	v_lshlrev_b32_e32 v26, 16, v85
	v_and_b32_e32 v27, 0xffff0000, v85
	v_pk_fma_f32 v[120:121], v[26:27], v[26:27], v[120:121]
	v_lshlrev_b32_e32 v26, 16, v86
	v_and_b32_e32 v27, 0xffff0000, v86
	v_pk_fma_f32 v[120:121], v[26:27], v[26:27], v[120:121]
	v_lshlrev_b32_e32 v26, 16, v87
	v_and_b32_e32 v27, 0xffff0000, v87
	v_pk_fma_f32 v[120:121], v[26:27], v[26:27], v[120:121]
	v_add_f32_e32 v6, v120, v121
	s_waitcnt vmcnt(0)
	v_lshlrev_b32_e32 v26, 16, v88
	v_and_b32_e32 v27, 0xffff0000, v88
	v_pk_mul_f32 v[122:123], v[26:27], v[26:27]
	v_lshlrev_b32_e32 v26, 16, v89
	v_and_b32_e32 v27, 0xffff0000, v89
	v_pk_fma_f32 v[122:123], v[26:27], v[26:27], v[122:123]
	v_lshlrev_b32_e32 v26, 16, v90
	v_and_b32_e32 v27, 0xffff0000, v90
	v_pk_fma_f32 v[122:123], v[26:27], v[26:27], v[122:123]
	v_lshlrev_b32_e32 v26, 16, v91
	v_and_b32_e32 v27, 0xffff0000, v91
	v_pk_fma_f32 v[122:123], v[26:27], v[26:27], v[122:123]
	v_lshlrev_b32_e32 v26, 16, v92
	v_and_b32_e32 v27, 0xffff0000, v92
	v_pk_fma_f32 v[122:123], v[26:27], v[26:27], v[122:123]
	v_lshlrev_b32_e32 v26, 16, v93
	v_and_b32_e32 v27, 0xffff0000, v93
	v_pk_fma_f32 v[122:123], v[26:27], v[26:27], v[122:123]
	v_lshlrev_b32_e32 v26, 16, v94
	v_and_b32_e32 v27, 0xffff0000, v94
	v_pk_fma_f32 v[122:123], v[26:27], v[26:27], v[122:123]
	v_lshlrev_b32_e32 v26, 16, v95
	v_and_b32_e32 v27, 0xffff0000, v95
	v_pk_fma_f32 v[122:123], v[26:27], v[26:27], v[122:123]
	v_add_f32_e32 v7, v122, v123
	ds_bpermute_b32 v28, v50, v4
	ds_bpermute_b32 v29, v50, v5
	ds_bpermute_b32 v30, v50, v6
	ds_bpermute_b32 v31, v50, v7
	s_waitcnt lgkmcnt(3)
	v_add_f32_e32 v4, v4, v28
	s_waitcnt lgkmcnt(2)
	v_add_f32_e32 v5, v5, v29
	s_waitcnt lgkmcnt(1)
	v_add_f32_e32 v6, v6, v30
	s_waitcnt lgkmcnt(0)
	v_add_f32_e32 v7, v7, v31
	ds_bpermute_b32 v28, v51, v4
	ds_bpermute_b32 v29, v51, v5
	ds_bpermute_b32 v30, v51, v6
	ds_bpermute_b32 v31, v51, v7
	s_waitcnt lgkmcnt(3)
	v_add_f32_e32 v4, v4, v28
	s_waitcnt lgkmcnt(2)
	v_add_f32_e32 v5, v5, v29
	s_waitcnt lgkmcnt(1)
	v_add_f32_e32 v6, v6, v30
	s_waitcnt lgkmcnt(0)
	v_add_f32_e32 v7, v7, v31
	ds_bpermute_b32 v28, v52, v4
	ds_bpermute_b32 v29, v52, v5
	ds_bpermute_b32 v30, v52, v6
	ds_bpermute_b32 v31, v52, v7
	s_waitcnt lgkmcnt(3)
	v_add_f32_e32 v4, v4, v28
	s_waitcnt lgkmcnt(2)
	v_add_f32_e32 v5, v5, v29
	s_waitcnt lgkmcnt(1)
	v_add_f32_e32 v6, v6, v30
	s_waitcnt lgkmcnt(0)
	v_add_f32_e32 v7, v7, v31
	ds_bpermute_b32 v28, v53, v4
	ds_bpermute_b32 v29, v53, v5
	ds_bpermute_b32 v30, v53, v6
	ds_bpermute_b32 v31, v53, v7
	s_waitcnt lgkmcnt(3)
	v_add_f32_e32 v4, v4, v28
	s_waitcnt lgkmcnt(2)
	v_add_f32_e32 v5, v5, v29
	s_waitcnt lgkmcnt(1)
	v_add_f32_e32 v6, v6, v30
	s_waitcnt lgkmcnt(0)
	v_add_f32_e32 v7, v7, v31
	ds_bpermute_b32 v28, v54, v4
	ds_bpermute_b32 v29, v54, v5
	ds_bpermute_b32 v30, v54, v6
	ds_bpermute_b32 v31, v54, v7
	s_waitcnt lgkmcnt(3)
	v_add_f32_e32 v4, v4, v28
	s_waitcnt lgkmcnt(2)
	v_add_f32_e32 v5, v5, v29
	s_waitcnt lgkmcnt(1)
	v_add_f32_e32 v6, v6, v30
	s_waitcnt lgkmcnt(0)
	v_add_f32_e32 v7, v7, v31
	ds_bpermute_b32 v28, v55, v4
	ds_bpermute_b32 v29, v55, v5
	ds_bpermute_b32 v30, v55, v6
	ds_bpermute_b32 v31, v55, v7
	s_waitcnt lgkmcnt(3)
	v_add_f32_e32 v4, v4, v28
	s_waitcnt lgkmcnt(2)
	v_add_f32_e32 v5, v5, v29
	s_waitcnt lgkmcnt(1)
	v_add_f32_e32 v6, v6, v30
	s_waitcnt lgkmcnt(0)
	v_add_f32_e32 v7, v7, v31
	v_fmamk_f32 v4, v4, 0x3a800000, v60
	v_fmamk_f32 v5, v5, 0x3a800000, v60
	v_fmamk_f32 v6, v6, 0x3a800000, v60
	v_fmamk_f32 v7, v7, 0x3a800000, v60
	v_rsq_f32_e32 v4, v4
	v_rsq_f32_e32 v5, v5
	v_rsq_f32_e32 v6, v6
	v_rsq_f32_e32 v7, v7
	s_nop 0
	v_lshlrev_b32_e32 v26, 16, v64
	v_and_b32_e32 v27, 0xffff0000, v64
	v_pk_mul_f32 v[26:27], v[26:27], v[4:5] op_sel_hi:[1,0]
	v_pk_fma_f32 v[26:27], v[96:97], v[26:27], v[112:113]
	v_cvt_pk_bf16_f32 v32, v26, v27
	v_lshlrev_b32_e32 v26, 16, v65
	v_and_b32_e32 v27, 0xffff0000, v65
	v_pk_mul_f32 v[26:27], v[26:27], v[4:5] op_sel_hi:[1,0]
	v_pk_fma_f32 v[26:27], v[98:99], v[26:27], v[114:115]
	v_cvt_pk_bf16_f32 v33, v26, v27
	v_lshlrev_b32_e32 v26, 16, v66
	v_and_b32_e32 v27, 0xffff0000, v66
	v_pk_mul_f32 v[26:27], v[26:27], v[4:5] op_sel_hi:[1,0]
	v_pk_fma_f32 v[26:27], v[100:101], v[26:27], v[116:117]
	v_cvt_pk_bf16_f32 v34, v26, v27
	v_lshlrev_b32_e32 v26, 16, v67
	v_and_b32_e32 v27, 0xffff0000, v67
	v_pk_mul_f32 v[26:27], v[26:27], v[4:5] op_sel_hi:[1,0]
	v_pk_fma_f32 v[26:27], v[102:103], v[26:27], v[118:119]
	v_cvt_pk_bf16_f32 v35, v26, v27
	global_store_dwordx4 v[16:17], v[32:35], off
	v_lshlrev_b32_e32 v26, 16, v68
	v_and_b32_e32 v27, 0xffff0000, v68
	v_pk_mul_f32 v[26:27], v[26:27], v[4:5] op_sel_hi:[1,0]
	v_pk_fma_f32 v[26:27], v[104:105], v[26:27], v[40:41]
	v_cvt_pk_bf16_f32 v36, v26, v27
	v_lshlrev_b32_e32 v26, 16, v69
	v_and_b32_e32 v27, 0xffff0000, v69
	v_pk_mul_f32 v[26:27], v[26:27], v[4:5] op_sel_hi:[1,0]
	v_pk_fma_f32 v[26:27], v[106:107], v[26:27], v[42:43]
	v_cvt_pk_bf16_f32 v37, v26, v27
	v_lshlrev_b32_e32 v26, 16, v70
	v_and_b32_e32 v27, 0xffff0000, v70
	v_pk_mul_f32 v[26:27], v[26:27], v[4:5] op_sel_hi:[1,0]
	v_pk_fma_f32 v[26:27], v[108:109], v[26:27], v[44:45]
	v_cvt_pk_bf16_f32 v38, v26, v27
	v_lshlrev_b32_e32 v26, 16, v71
	v_and_b32_e32 v27, 0xffff0000, v71
	v_pk_mul_f32 v[26:27], v[26:27], v[4:5] op_sel_hi:[1,0]
	v_pk_fma_f32 v[26:27], v[110:111], v[26:27], v[46:47]
	v_cvt_pk_bf16_f32 v39, v26, v27
	global_store_dwordx4 v[16:17], v[36:39], off offset:1024
	v_lshlrev_b32_e32 v26, 16, v72
	v_and_b32_e32 v27, 0xffff0000, v72
	v_pk_mul_f32 v[26:27], v[26:27], v[4:5] op_sel:[0,1] op_sel_hi:[1,1]
	v_pk_fma_f32 v[26:27], v[96:97], v[26:27], v[112:113]
	v_cvt_pk_bf16_f32 v32, v26, v27
	v_lshlrev_b32_e32 v26, 16, v73
	v_and_b32_e32 v27, 0xffff0000, v73
	v_pk_mul_f32 v[26:27], v[26:27], v[4:5] op_sel:[0,1] op_sel_hi:[1,1]
	v_pk_fma_f32 v[26:27], v[98:99], v[26:27], v[114:115]
	v_cvt_pk_bf16_f32 v33, v26, v27
	v_lshlrev_b32_e32 v26, 16, v74
	v_and_b32_e32 v27, 0xffff0000, v74
	v_pk_mul_f32 v[26:27], v[26:27], v[4:5] op_sel:[0,1] op_sel_hi:[1,1]
	v_pk_fma_f32 v[26:27], v[100:101], v[26:27], v[116:117]
	v_cvt_pk_bf16_f32 v34, v26, v27
	v_lshlrev_b32_e32 v26, 16, v75
	v_and_b32_e32 v27, 0xffff0000, v75
	v_pk_mul_f32 v[26:27], v[26:27], v[4:5] op_sel:[0,1] op_sel_hi:[1,1]
	v_pk_fma_f32 v[26:27], v[102:103], v[26:27], v[118:119]
	v_cvt_pk_bf16_f32 v35, v26, v27
	global_store_dwordx4 v[16:17], v[32:35], off offset:2048
	v_lshlrev_b32_e32 v26, 16, v76
	v_and_b32_e32 v27, 0xffff0000, v76
	v_pk_mul_f32 v[26:27], v[26:27], v[4:5] op_sel:[0,1] op_sel_hi:[1,1]
	v_pk_fma_f32 v[26:27], v[104:105], v[26:27], v[40:41]
	v_cvt_pk_bf16_f32 v36, v26, v27
	v_lshlrev_b32_e32 v26, 16, v77
	v_and_b32_e32 v27, 0xffff0000, v77
	v_pk_mul_f32 v[26:27], v[26:27], v[4:5] op_sel:[0,1] op_sel_hi:[1,1]
	v_pk_fma_f32 v[26:27], v[106:107], v[26:27], v[42:43]
	v_cvt_pk_bf16_f32 v37, v26, v27
	v_lshlrev_b32_e32 v26, 16, v78
	v_and_b32_e32 v27, 0xffff0000, v78
	v_pk_mul_f32 v[26:27], v[26:27], v[4:5] op_sel:[0,1] op_sel_hi:[1,1]
	v_pk_fma_f32 v[26:27], v[108:109], v[26:27], v[44:45]
	v_cvt_pk_bf16_f32 v38, v26, v27
	v_lshlrev_b32_e32 v26, 16, v79
	v_and_b32_e32 v27, 0xffff0000, v79
	v_pk_mul_f32 v[26:27], v[26:27], v[4:5] op_sel:[0,1] op_sel_hi:[1,1]
	v_pk_fma_f32 v[26:27], v[110:111], v[26:27], v[46:47]
	v_cvt_pk_bf16_f32 v39, v26, v27
	global_store_dwordx4 v[16:17], v[36:39], off offset:3072
	v_lshlrev_b32_e32 v26, 16, v80
	v_and_b32_e32 v27, 0xffff0000, v80
	v_pk_mul_f32 v[26:27], v[26:27], v[6:7] op_sel_hi:[1,0]
	v_pk_fma_f32 v[26:27], v[96:97], v[26:27], v[112:113]
	v_cvt_pk_bf16_f32 v32, v26, v27
	v_lshlrev_b32_e32 v26, 16, v81
	v_and_b32_e32 v27, 0xffff0000, v81
	v_pk_mul_f32 v[26:27], v[26:27], v[6:7] op_sel_hi:[1,0]
	v_pk_fma_f32 v[26:27], v[98:99], v[26:27], v[114:115]
	v_cvt_pk_bf16_f32 v33, v26, v27
	v_lshlrev_b32_e32 v26, 16, v82
	v_and_b32_e32 v27, 0xffff0000, v82
	v_pk_mul_f32 v[26:27], v[26:27], v[6:7] op_sel_hi:[1,0]
	v_pk_fma_f32 v[26:27], v[100:101], v[26:27], v[116:117]
	v_cvt_pk_bf16_f32 v34, v26, v27
	v_lshlrev_b32_e32 v26, 16, v83
	v_and_b32_e32 v27, 0xffff0000, v83
	v_pk_mul_f32 v[26:27], v[26:27], v[6:7] op_sel_hi:[1,0]
	v_pk_fma_f32 v[26:27], v[102:103], v[26:27], v[118:119]
	v_cvt_pk_bf16_f32 v35, v26, v27
	global_store_dwordx4 v[10:11], v[32:35], off
	v_lshlrev_b32_e32 v26, 16, v84
	v_and_b32_e32 v27, 0xffff0000, v84
	v_pk_mul_f32 v[26:27], v[26:27], v[6:7] op_sel_hi:[1,0]
	v_pk_fma_f32 v[26:27], v[104:105], v[26:27], v[40:41]
	v_cvt_pk_bf16_f32 v36, v26, v27
	v_lshlrev_b32_e32 v26, 16, v85
	v_and_b32_e32 v27, 0xffff0000, v85
	v_pk_mul_f32 v[26:27], v[26:27], v[6:7] op_sel_hi:[1,0]
	v_pk_fma_f32 v[26:27], v[106:107], v[26:27], v[42:43]
	v_cvt_pk_bf16_f32 v37, v26, v27
	v_lshlrev_b32_e32 v26, 16, v86
	v_and_b32_e32 v27, 0xffff0000, v86
	v_pk_mul_f32 v[26:27], v[26:27], v[6:7] op_sel_hi:[1,0]
	v_pk_fma_f32 v[26:27], v[108:109], v[26:27], v[44:45]
	v_cvt_pk_bf16_f32 v38, v26, v27
	v_lshlrev_b32_e32 v26, 16, v87
	v_and_b32_e32 v27, 0xffff0000, v87
	v_pk_mul_f32 v[26:27], v[26:27], v[6:7] op_sel_hi:[1,0]
	v_pk_fma_f32 v[26:27], v[110:111], v[26:27], v[46:47]
	v_cvt_pk_bf16_f32 v39, v26, v27
	global_store_dwordx4 v[10:11], v[36:39], off offset:1024
	v_lshlrev_b32_e32 v26, 16, v88
	v_and_b32_e32 v27, 0xffff0000, v88
	v_pk_mul_f32 v[26:27], v[26:27], v[6:7] op_sel:[0,1] op_sel_hi:[1,1]
	v_pk_fma_f32 v[26:27], v[96:97], v[26:27], v[112:113]
	v_cvt_pk_bf16_f32 v32, v26, v27
	v_lshlrev_b32_e32 v26, 16, v89
	v_and_b32_e32 v27, 0xffff0000, v89
	v_pk_mul_f32 v[26:27], v[26:27], v[6:7] op_sel:[0,1] op_sel_hi:[1,1]
	v_pk_fma_f32 v[26:27], v[98:99], v[26:27], v[114:115]
	v_cvt_pk_bf16_f32 v33, v26, v27
	v_lshlrev_b32_e32 v26, 16, v90
	v_and_b32_e32 v27, 0xffff0000, v90
	v_pk_mul_f32 v[26:27], v[26:27], v[6:7] op_sel:[0,1] op_sel_hi:[1,1]
	v_pk_fma_f32 v[26:27], v[100:101], v[26:27], v[116:117]
	v_cvt_pk_bf16_f32 v34, v26, v27
	v_lshlrev_b32_e32 v26, 16, v91
	v_and_b32_e32 v27, 0xffff0000, v91
	v_pk_mul_f32 v[26:27], v[26:27], v[6:7] op_sel:[0,1] op_sel_hi:[1,1]
	v_pk_fma_f32 v[26:27], v[102:103], v[26:27], v[118:119]
	v_cvt_pk_bf16_f32 v35, v26, v27
	global_store_dwordx4 v[10:11], v[32:35], off offset:2048
	v_lshlrev_b32_e32 v26, 16, v92
	v_and_b32_e32 v27, 0xffff0000, v92
	v_pk_mul_f32 v[26:27], v[26:27], v[6:7] op_sel:[0,1] op_sel_hi:[1,1]
	v_pk_fma_f32 v[26:27], v[104:105], v[26:27], v[40:41]
	v_cvt_pk_bf16_f32 v36, v26, v27
	v_lshlrev_b32_e32 v26, 16, v93
	v_and_b32_e32 v27, 0xffff0000, v93
	v_pk_mul_f32 v[26:27], v[26:27], v[6:7] op_sel:[0,1] op_sel_hi:[1,1]
	v_pk_fma_f32 v[26:27], v[106:107], v[26:27], v[42:43]
	v_cvt_pk_bf16_f32 v37, v26, v27
	v_lshlrev_b32_e32 v26, 16, v94
	v_and_b32_e32 v27, 0xffff0000, v94
	v_pk_mul_f32 v[26:27], v[26:27], v[6:7] op_sel:[0,1] op_sel_hi:[1,1]
	v_pk_fma_f32 v[26:27], v[108:109], v[26:27], v[44:45]
	v_cvt_pk_bf16_f32 v38, v26, v27
	v_lshlrev_b32_e32 v26, 16, v95
	v_and_b32_e32 v27, 0xffff0000, v95
	v_pk_mul_f32 v[26:27], v[26:27], v[6:7] op_sel:[0,1] op_sel_hi:[1,1]
	v_pk_fma_f32 v[26:27], v[110:111], v[26:27], v[46:47]
	v_cvt_pk_bf16_f32 v39, v26, v27
	global_store_dwordx4 v[10:11], v[36:39], off offset:3072
	s_add_i32 s35, s35, s84
	s_cmpk_gt_i32 s35, 0x1ff
	s_barrier
	s_cbranch_scc1 .LBB0_850

.LBB0_1191:
	s_or_b64 exec, exec, s[16:17]
	v_and_b32_e32 v10, 63, v0
	v_lshlrev_b32_e32 v62, 5, v10
	v_lshlrev_b32_e32 v11, 3, v10
	v_add_u32_e32 v12, s30, v1
	v_lshl_add_u32 v12, v12, 11, v11
	v_mov_b32_e32 v13, 0
	v_lshl_add_u64 v[14:15], v[12:13], 0, v[20:21]
	v_lshl_add_u64 v[16:17], v[12:13], 0, v[22:23]
	v_add_u32_e32 v12, 0x1000, v12
	v_lshl_add_u64 v[8:9], v[12:13], 0, v[20:21]
	v_lshl_add_u64 v[10:11], v[12:13], 0, v[22:23]
	global_load_dwordx4 v[64:67], v[14:15], off
	global_load_dwordx4 v[68:71], v[14:15], off offset:1024
	global_load_dwordx4 v[72:75], v[14:15], off offset:2048
	global_load_dwordx4 v[76:79], v[14:15], off offset:3072
	global_load_dwordx4 v[80:83], v[8:9], off
	global_load_dwordx4 v[84:87], v[8:9], off offset:1024
	global_load_dwordx4 v[88:91], v[8:9], off offset:2048
	global_load_dwordx4 v[92:95], v[8:9], off offset:3072
	s_waitcnt lgkmcnt(0)
	s_barrier
	ds_read_b128 v[96:99], v62 offset:4096
	ds_read_b128 v[100:103], v62 offset:4112
	ds_read_b128 v[104:107], v62 offset:6144
	ds_read_b128 v[108:111], v62 offset:6160
	ds_read_b128 v[112:115], v62
	ds_read_b128 v[116:119], v62 offset:16
	ds_read_b128 v[40:43], v62 offset:2048
	ds_read_b128 v[44:47], v62 offset:2064
	s_waitcnt vmcnt(6)
	v_lshlrev_b32_e32 v26, 16, v64
	v_and_b32_e32 v27, 0xffff0000, v64
	v_pk_mul_f32 v[2:3], v[26:27], v[26:27]
	v_lshlrev_b32_e32 v26, 16, v65
	v_and_b32_e32 v27, 0xffff0000, v65
	v_pk_fma_f32 v[2:3], v[26:27], v[26:27], v[2:3]
	v_lshlrev_b32_e32 v26, 16, v66
	v_and_b32_e32 v27, 0xffff0000, v66
	v_pk_fma_f32 v[2:3], v[26:27], v[26:27], v[2:3]
	v_lshlrev_b32_e32 v26, 16, v67
	v_and_b32_e32 v27, 0xffff0000, v67
	v_pk_fma_f32 v[2:3], v[26:27], v[26:27], v[2:3]
	v_lshlrev_b32_e32 v26, 16, v68
	v_and_b32_e32 v27, 0xffff0000, v68
	v_pk_fma_f32 v[2:3], v[26:27], v[26:27], v[2:3]
	v_lshlrev_b32_e32 v26, 16, v69
	v_and_b32_e32 v27, 0xffff0000, v69
	v_pk_fma_f32 v[2:3], v[26:27], v[26:27], v[2:3]
	v_lshlrev_b32_e32 v26, 16, v70
	v_and_b32_e32 v27, 0xffff0000, v70
	v_pk_fma_f32 v[2:3], v[26:27], v[26:27], v[2:3]
	v_lshlrev_b32_e32 v26, 16, v71
	v_and_b32_e32 v27, 0xffff0000, v71
	v_pk_fma_f32 v[2:3], v[26:27], v[26:27], v[2:3]
	v_add_f32_e32 v4, v2, v3
	s_waitcnt vmcnt(4)
	v_lshlrev_b32_e32 v26, 16, v72
	v_and_b32_e32 v27, 0xffff0000, v72
	v_pk_mul_f32 v[24:25], v[26:27], v[26:27]
	v_lshlrev_b32_e32 v26, 16, v73
	v_and_b32_e32 v27, 0xffff0000, v73
	v_pk_fma_f32 v[24:25], v[26:27], v[26:27], v[24:25]
	v_lshlrev_b32_e32 v26, 16, v74
	v_and_b32_e32 v27, 0xffff0000, v74
	v_pk_fma_f32 v[24:25], v[26:27], v[26:27], v[24:25]
	v_lshlrev_b32_e32 v26, 16, v75
	v_and_b32_e32 v27, 0xffff0000, v75
	v_pk_fma_f32 v[24:25], v[26:27], v[26:27], v[24:25]
	v_lshlrev_b32_e32 v26, 16, v76
	v_and_b32_e32 v27, 0xffff0000, v76
	v_pk_fma_f32 v[24:25], v[26:27], v[26:27], v[24:25]
	v_lshlrev_b32_e32 v26, 16, v77
	v_and_b32_e32 v27, 0xffff0000, v77
	v_pk_fma_f32 v[24:25], v[26:27], v[26:27], v[24:25]
	v_lshlrev_b32_e32 v26, 16, v78
	v_and_b32_e32 v27, 0xffff0000, v78
	v_pk_fma_f32 v[24:25], v[26:27], v[26:27], v[24:25]
	v_lshlrev_b32_e32 v26, 16, v79
	v_and_b32_e32 v27, 0xffff0000, v79
	v_pk_fma_f32 v[24:25], v[26:27], v[26:27], v[24:25]
	v_add_f32_e32 v5, v24, v25
	s_waitcnt vmcnt(2)
	v_lshlrev_b32_e32 v26, 16, v80
	v_and_b32_e32 v27, 0xffff0000, v80
	v_pk_mul_f32 v[120:121], v[26:27], v[26:27]
	v_lshlrev_b32_e32 v26, 16, v81
	v_and_b32_e32 v27, 0xffff0000, v81
	v_pk_fma_f32 v[120:121], v[26:27], v[26:27], v[120:121]
	v_lshlrev_b32_e32 v26, 16, v82
	v_and_b32_e32 v27, 0xffff0000, v82
	v_pk_fma_f32 v[120:121], v[26:27], v[26:27], v[120:121]
	v_lshlrev_b32_e32 v26, 16, v83
	v_and_b32_e32 v27, 0xffff0000, v83
	v_pk_fma_f32 v[120:121], v[26:27], v[26:27], v[120:121]
	v_lshlrev_b32_e32 v26, 16, v84
	v_and_b32_e32 v27, 0xffff0000, v84
	v_pk_fma_f32 v[120:121], v[26:27], v[26:27], v[120:121]
	v_lshlrev_b32_e32 v26, 16, v85
	v_and_b32_e32 v27, 0xffff0000, v85
	v_pk_fma_f32 v[120:121], v[26:27], v[26:27], v[120:121]
	v_lshlrev_b32_e32 v26, 16, v86
	v_and_b32_e32 v27, 0xffff0000, v86
	v_pk_fma_f32 v[120:121], v[26:27], v[26:27], v[120:121]
	v_lshlrev_b32_e32 v26, 16, v87
	v_and_b32_e32 v27, 0xffff0000, v87
	v_pk_fma_f32 v[120:121], v[26:27], v[26:27], v[120:121]
	v_add_f32_e32 v6, v120, v121
	s_waitcnt vmcnt(0)
	v_lshlrev_b32_e32 v26, 16, v88
	v_and_b32_e32 v27, 0xffff0000, v88
	v_pk_mul_f32 v[122:123], v[26:27], v[26:27]
	v_lshlrev_b32_e32 v26, 16, v89
	v_and_b32_e32 v27, 0xffff0000, v89
	v_pk_fma_f32 v[122:123], v[26:27], v[26:27], v[122:123]
	v_lshlrev_b32_e32 v26, 16, v90
	v_and_b32_e32 v27, 0xffff0000, v90
	v_pk_fma_f32 v[122:123], v[26:27], v[26:27], v[122:123]
	v_lshlrev_b32_e32 v26, 16, v91
	v_and_b32_e32 v27, 0xffff0000, v91
	v_pk_fma_f32 v[122:123], v[26:27], v[26:27], v[122:123]
	v_lshlrev_b32_e32 v26, 16, v92
	v_and_b32_e32 v27, 0xffff0000, v92
	v_pk_fma_f32 v[122:123], v[26:27], v[26:27], v[122:123]
	v_lshlrev_b32_e32 v26, 16, v93
	v_and_b32_e32 v27, 0xffff0000, v93
	v_pk_fma_f32 v[122:123], v[26:27], v[26:27], v[122:123]
	v_lshlrev_b32_e32 v26, 16, v94
	v_and_b32_e32 v27, 0xffff0000, v94
	v_pk_fma_f32 v[122:123], v[26:27], v[26:27], v[122:123]
	v_lshlrev_b32_e32 v26, 16, v95
	v_and_b32_e32 v27, 0xffff0000, v95
	v_pk_fma_f32 v[122:123], v[26:27], v[26:27], v[122:123]
	v_add_f32_e32 v7, v122, v123
	ds_bpermute_b32 v28, v50, v4
	ds_bpermute_b32 v29, v50, v5
	ds_bpermute_b32 v30, v50, v6
	ds_bpermute_b32 v31, v50, v7
	s_waitcnt lgkmcnt(3)
	v_add_f32_e32 v4, v4, v28
	s_waitcnt lgkmcnt(2)
	v_add_f32_e32 v5, v5, v29
	s_waitcnt lgkmcnt(1)
	v_add_f32_e32 v6, v6, v30
	s_waitcnt lgkmcnt(0)
	v_add_f32_e32 v7, v7, v31
	ds_bpermute_b32 v28, v51, v4
	ds_bpermute_b32 v29, v51, v5
	ds_bpermute_b32 v30, v51, v6
	ds_bpermute_b32 v31, v51, v7
	s_waitcnt lgkmcnt(3)
	v_add_f32_e32 v4, v4, v28
	s_waitcnt lgkmcnt(2)
	v_add_f32_e32 v5, v5, v29
	s_waitcnt lgkmcnt(1)
	v_add_f32_e32 v6, v6, v30
	s_waitcnt lgkmcnt(0)
	v_add_f32_e32 v7, v7, v31
	ds_bpermute_b32 v28, v52, v4
	ds_bpermute_b32 v29, v52, v5
	ds_bpermute_b32 v30, v52, v6
	ds_bpermute_b32 v31, v52, v7
	s_waitcnt lgkmcnt(3)
	v_add_f32_e32 v4, v4, v28
	s_waitcnt lgkmcnt(2)
	v_add_f32_e32 v5, v5, v29
	s_waitcnt lgkmcnt(1)
	v_add_f32_e32 v6, v6, v30
	s_waitcnt lgkmcnt(0)
	v_add_f32_e32 v7, v7, v31
	ds_bpermute_b32 v28, v53, v4
	ds_bpermute_b32 v29, v53, v5
	ds_bpermute_b32 v30, v53, v6
	ds_bpermute_b32 v31, v53, v7
	s_waitcnt lgkmcnt(3)
	v_add_f32_e32 v4, v4, v28
	s_waitcnt lgkmcnt(2)
	v_add_f32_e32 v5, v5, v29
	s_waitcnt lgkmcnt(1)
	v_add_f32_e32 v6, v6, v30
	s_waitcnt lgkmcnt(0)
	v_add_f32_e32 v7, v7, v31
	ds_bpermute_b32 v28, v54, v4
	ds_bpermute_b32 v29, v54, v5
	ds_bpermute_b32 v30, v54, v6
	ds_bpermute_b32 v31, v54, v7
	s_waitcnt lgkmcnt(3)
	v_add_f32_e32 v4, v4, v28
	s_waitcnt lgkmcnt(2)
	v_add_f32_e32 v5, v5, v29
	s_waitcnt lgkmcnt(1)
	v_add_f32_e32 v6, v6, v30
	s_waitcnt lgkmcnt(0)
	v_add_f32_e32 v7, v7, v31
	ds_bpermute_b32 v28, v55, v4
	ds_bpermute_b32 v29, v55, v5
	ds_bpermute_b32 v30, v55, v6
	ds_bpermute_b32 v31, v55, v7
	s_waitcnt lgkmcnt(3)
	v_add_f32_e32 v4, v4, v28
	s_waitcnt lgkmcnt(2)
	v_add_f32_e32 v5, v5, v29
	s_waitcnt lgkmcnt(1)
	v_add_f32_e32 v6, v6, v30
	s_waitcnt lgkmcnt(0)
	v_add_f32_e32 v7, v7, v31
	v_fmamk_f32 v4, v4, 0x3a800000, v60
	v_fmamk_f32 v5, v5, 0x3a800000, v60
	v_fmamk_f32 v6, v6, 0x3a800000, v60
	v_fmamk_f32 v7, v7, 0x3a800000, v60
	v_rsq_f32_e32 v4, v4
	v_rsq_f32_e32 v5, v5
	v_rsq_f32_e32 v6, v6
	v_rsq_f32_e32 v7, v7
	s_nop 0
	v_lshlrev_b32_e32 v26, 16, v64
	v_and_b32_e32 v27, 0xffff0000, v64
	v_pk_mul_f32 v[26:27], v[26:27], v[4:5] op_sel_hi:[1,0]
	v_pk_fma_f32 v[26:27], v[96:97], v[26:27], v[112:113]
	v_cvt_pk_bf16_f32 v32, v26, v27
	v_lshlrev_b32_e32 v26, 16, v65
	v_and_b32_e32 v27, 0xffff0000, v65
	v_pk_mul_f32 v[26:27], v[26:27], v[4:5] op_sel_hi:[1,0]
	v_pk_fma_f32 v[26:27], v[98:99], v[26:27], v[114:115]
	v_cvt_pk_bf16_f32 v33, v26, v27
	v_lshlrev_b32_e32 v26, 16, v66
	v_and_b32_e32 v27, 0xffff0000, v66
	v_pk_mul_f32 v[26:27], v[26:27], v[4:5] op_sel_hi:[1,0]
	v_pk_fma_f32 v[26:27], v[100:101], v[26:27], v[116:117]
	v_cvt_pk_bf16_f32 v34, v26, v27
	v_lshlrev_b32_e32 v26, 16, v67
	v_and_b32_e32 v27, 0xffff0000, v67
	v_pk_mul_f32 v[26:27], v[26:27], v[4:5] op_sel_hi:[1,0]
	v_pk_fma_f32 v[26:27], v[102:103], v[26:27], v[118:119]
	v_cvt_pk_bf16_f32 v35, v26, v27
	global_store_dwordx4 v[16:17], v[32:35], off
	v_lshlrev_b32_e32 v26, 16, v68
	v_and_b32_e32 v27, 0xffff0000, v68
	v_pk_mul_f32 v[26:27], v[26:27], v[4:5] op_sel_hi:[1,0]
	v_pk_fma_f32 v[26:27], v[104:105], v[26:27], v[40:41]
	v_cvt_pk_bf16_f32 v36, v26, v27
	v_lshlrev_b32_e32 v26, 16, v69
	v_and_b32_e32 v27, 0xffff0000, v69
	v_pk_mul_f32 v[26:27], v[26:27], v[4:5] op_sel_hi:[1,0]
	v_pk_fma_f32 v[26:27], v[106:107], v[26:27], v[42:43]
	v_cvt_pk_bf16_f32 v37, v26, v27
	v_lshlrev_b32_e32 v26, 16, v70
	v_and_b32_e32 v27, 0xffff0000, v70
	v_pk_mul_f32 v[26:27], v[26:27], v[4:5] op_sel_hi:[1,0]
	v_pk_fma_f32 v[26:27], v[108:109], v[26:27], v[44:45]
	v_cvt_pk_bf16_f32 v38, v26, v27
	v_lshlrev_b32_e32 v26, 16, v71
	v_and_b32_e32 v27, 0xffff0000, v71
	v_pk_mul_f32 v[26:27], v[26:27], v[4:5] op_sel_hi:[1,0]
	v_pk_fma_f32 v[26:27], v[110:111], v[26:27], v[46:47]
	v_cvt_pk_bf16_f32 v39, v26, v27
	global_store_dwordx4 v[16:17], v[36:39], off offset:1024
	v_lshlrev_b32_e32 v26, 16, v72
	v_and_b32_e32 v27, 0xffff0000, v72
	v_pk_mul_f32 v[26:27], v[26:27], v[4:5] op_sel:[0,1] op_sel_hi:[1,1]
	v_pk_fma_f32 v[26:27], v[96:97], v[26:27], v[112:113]
	v_cvt_pk_bf16_f32 v32, v26, v27
	v_lshlrev_b32_e32 v26, 16, v73
	v_and_b32_e32 v27, 0xffff0000, v73
	v_pk_mul_f32 v[26:27], v[26:27], v[4:5] op_sel:[0,1] op_sel_hi:[1,1]
	v_pk_fma_f32 v[26:27], v[98:99], v[26:27], v[114:115]
	v_cvt_pk_bf16_f32 v33, v26, v27
	v_lshlrev_b32_e32 v26, 16, v74
	v_and_b32_e32 v27, 0xffff0000, v74
	v_pk_mul_f32 v[26:27], v[26:27], v[4:5] op_sel:[0,1] op_sel_hi:[1,1]
	v_pk_fma_f32 v[26:27], v[100:101], v[26:27], v[116:117]
	v_cvt_pk_bf16_f32 v34, v26, v27
	v_lshlrev_b32_e32 v26, 16, v75
	v_and_b32_e32 v27, 0xffff0000, v75
	v_pk_mul_f32 v[26:27], v[26:27], v[4:5] op_sel:[0,1] op_sel_hi:[1,1]
	v_pk_fma_f32 v[26:27], v[102:103], v[26:27], v[118:119]
	v_cvt_pk_bf16_f32 v35, v26, v27
	global_store_dwordx4 v[16:17], v[32:35], off offset:2048
	v_lshlrev_b32_e32 v26, 16, v76
	v_and_b32_e32 v27, 0xffff0000, v76
	v_pk_mul_f32 v[26:27], v[26:27], v[4:5] op_sel:[0,1] op_sel_hi:[1,1]
	v_pk_fma_f32 v[26:27], v[104:105], v[26:27], v[40:41]
	v_cvt_pk_bf16_f32 v36, v26, v27
	v_lshlrev_b32_e32 v26, 16, v77
	v_and_b32_e32 v27, 0xffff0000, v77
	v_pk_mul_f32 v[26:27], v[26:27], v[4:5] op_sel:[0,1] op_sel_hi:[1,1]
	v_pk_fma_f32 v[26:27], v[106:107], v[26:27], v[42:43]
	v_cvt_pk_bf16_f32 v37, v26, v27
	v_lshlrev_b32_e32 v26, 16, v78
	v_and_b32_e32 v27, 0xffff0000, v78
	v_pk_mul_f32 v[26:27], v[26:27], v[4:5] op_sel:[0,1] op_sel_hi:[1,1]
	v_pk_fma_f32 v[26:27], v[108:109], v[26:27], v[44:45]
	v_cvt_pk_bf16_f32 v38, v26, v27
	v_lshlrev_b32_e32 v26, 16, v79
	v_and_b32_e32 v27, 0xffff0000, v79
	v_pk_mul_f32 v[26:27], v[26:27], v[4:5] op_sel:[0,1] op_sel_hi:[1,1]
	v_pk_fma_f32 v[26:27], v[110:111], v[26:27], v[46:47]
	v_cvt_pk_bf16_f32 v39, v26, v27
	global_store_dwordx4 v[16:17], v[36:39], off offset:3072
	v_lshlrev_b32_e32 v26, 16, v80
	v_and_b32_e32 v27, 0xffff0000, v80
	v_pk_mul_f32 v[26:27], v[26:27], v[6:7] op_sel_hi:[1,0]
	v_pk_fma_f32 v[26:27], v[96:97], v[26:27], v[112:113]
	v_cvt_pk_bf16_f32 v32, v26, v27
	v_lshlrev_b32_e32 v26, 16, v81
	v_and_b32_e32 v27, 0xffff0000, v81
	v_pk_mul_f32 v[26:27], v[26:27], v[6:7] op_sel_hi:[1,0]
	v_pk_fma_f32 v[26:27], v[98:99], v[26:27], v[114:115]
	v_cvt_pk_bf16_f32 v33, v26, v27
	v_lshlrev_b32_e32 v26, 16, v82
	v_and_b32_e32 v27, 0xffff0000, v82
	v_pk_mul_f32 v[26:27], v[26:27], v[6:7] op_sel_hi:[1,0]
	v_pk_fma_f32 v[26:27], v[100:101], v[26:27], v[116:117]
	v_cvt_pk_bf16_f32 v34, v26, v27
	v_lshlrev_b32_e32 v26, 16, v83
	v_and_b32_e32 v27, 0xffff0000, v83
	v_pk_mul_f32 v[26:27], v[26:27], v[6:7] op_sel_hi:[1,0]
	v_pk_fma_f32 v[26:27], v[102:103], v[26:27], v[118:119]
	v_cvt_pk_bf16_f32 v35, v26, v27
	global_store_dwordx4 v[10:11], v[32:35], off
	v_lshlrev_b32_e32 v26, 16, v84
	v_and_b32_e32 v27, 0xffff0000, v84
	v_pk_mul_f32 v[26:27], v[26:27], v[6:7] op_sel_hi:[1,0]
	v_pk_fma_f32 v[26:27], v[104:105], v[26:27], v[40:41]
	v_cvt_pk_bf16_f32 v36, v26, v27
	v_lshlrev_b32_e32 v26, 16, v85
	v_and_b32_e32 v27, 0xffff0000, v85
	v_pk_mul_f32 v[26:27], v[26:27], v[6:7] op_sel_hi:[1,0]
	v_pk_fma_f32 v[26:27], v[106:107], v[26:27], v[42:43]
	v_cvt_pk_bf16_f32 v37, v26, v27
	v_lshlrev_b32_e32 v26, 16, v86
	v_and_b32_e32 v27, 0xffff0000, v86
	v_pk_mul_f32 v[26:27], v[26:27], v[6:7] op_sel_hi:[1,0]
	v_pk_fma_f32 v[26:27], v[108:109], v[26:27], v[44:45]
	v_cvt_pk_bf16_f32 v38, v26, v27
	v_lshlrev_b32_e32 v26, 16, v87
	v_and_b32_e32 v27, 0xffff0000, v87
	v_pk_mul_f32 v[26:27], v[26:27], v[6:7] op_sel_hi:[1,0]
	v_pk_fma_f32 v[26:27], v[110:111], v[26:27], v[46:47]
	v_cvt_pk_bf16_f32 v39, v26, v27
	global_store_dwordx4 v[10:11], v[36:39], off offset:1024
	v_lshlrev_b32_e32 v26, 16, v88
	v_and_b32_e32 v27, 0xffff0000, v88
	v_pk_mul_f32 v[26:27], v[26:27], v[6:7] op_sel:[0,1] op_sel_hi:[1,1]
	v_pk_fma_f32 v[26:27], v[96:97], v[26:27], v[112:113]
	v_cvt_pk_bf16_f32 v32, v26, v27
	v_lshlrev_b32_e32 v26, 16, v89
	v_and_b32_e32 v27, 0xffff0000, v89
	v_pk_mul_f32 v[26:27], v[26:27], v[6:7] op_sel:[0,1] op_sel_hi:[1,1]
	v_pk_fma_f32 v[26:27], v[98:99], v[26:27], v[114:115]
	v_cvt_pk_bf16_f32 v33, v26, v27
	v_lshlrev_b32_e32 v26, 16, v90
	v_and_b32_e32 v27, 0xffff0000, v90
	v_pk_mul_f32 v[26:27], v[26:27], v[6:7] op_sel:[0,1] op_sel_hi:[1,1]
	v_pk_fma_f32 v[26:27], v[100:101], v[26:27], v[116:117]
	v_cvt_pk_bf16_f32 v34, v26, v27
	v_lshlrev_b32_e32 v26, 16, v91
	v_and_b32_e32 v27, 0xffff0000, v91
	v_pk_mul_f32 v[26:27], v[26:27], v[6:7] op_sel:[0,1] op_sel_hi:[1,1]
	v_pk_fma_f32 v[26:27], v[102:103], v[26:27], v[118:119]
	v_cvt_pk_bf16_f32 v35, v26, v27
	global_store_dwordx4 v[10:11], v[32:35], off offset:2048
	v_lshlrev_b32_e32 v26, 16, v92
	v_and_b32_e32 v27, 0xffff0000, v92
	v_pk_mul_f32 v[26:27], v[26:27], v[6:7] op_sel:[0,1] op_sel_hi:[1,1]
	v_pk_fma_f32 v[26:27], v[104:105], v[26:27], v[40:41]
	v_cvt_pk_bf16_f32 v36, v26, v27
	v_lshlrev_b32_e32 v26, 16, v93
	v_and_b32_e32 v27, 0xffff0000, v93
	v_pk_mul_f32 v[26:27], v[26:27], v[6:7] op_sel:[0,1] op_sel_hi:[1,1]
	v_pk_fma_f32 v[26:27], v[106:107], v[26:27], v[42:43]
	v_cvt_pk_bf16_f32 v37, v26, v27
	v_lshlrev_b32_e32 v26, 16, v94
	v_and_b32_e32 v27, 0xffff0000, v94
	v_pk_mul_f32 v[26:27], v[26:27], v[6:7] op_sel:[0,1] op_sel_hi:[1,1]
	v_pk_fma_f32 v[26:27], v[108:109], v[26:27], v[44:45]
	v_cvt_pk_bf16_f32 v38, v26, v27
	v_lshlrev_b32_e32 v26, 16, v95
	v_and_b32_e32 v27, 0xffff0000, v95
	v_pk_mul_f32 v[26:27], v[26:27], v[6:7] op_sel:[0,1] op_sel_hi:[1,1]
	v_pk_fma_f32 v[26:27], v[110:111], v[26:27], v[46:47]
	v_cvt_pk_bf16_f32 v39, v26, v27
	global_store_dwordx4 v[10:11], v[36:39], off offset:3072
	s_add_i32 s29, s29, s84
	s_cmpk_gt_i32 s29, 0x1ff
	s_barrier
	s_cbranch_scc1 .LBB0_1207
